# K3 + no-op setprio 0/1 pairs between the two MFMA blocks removed in the ff1 and out/ff2 K-loops
# baseline (speedup 1.0000x reference)
.LBB0_234:
	s_add_u32 s26, s6, 0xfffc0080
	s_addc_u32 s27, s7, -1
	s_add_i32 s90, 0, 0x10000
	s_cmp_eq_u32 s89, 12
	s_cselect_b32 s61, s31, s27
	s_cselect_b32 s60, s80, s26
	v_add_u32_e32 v144, s90, v146
	s_cselect_b32 s39, s15, s88
	s_cselect_b32 s38, s86, s87
	s_add_i32 s91, 0, 0x14000
	.p2align 6
	ds_read_b128 v[140:143], v144
	ds_read_b128 v[148:151], v144 offset:1024
	ds_read_b128 v[152:155], v144 offset:2048
	ds_read_b128 v[156:159], v144 offset:3072
	v_add_u32_e32 v144, s91, v146
	ds_read_b128 v[160:163], v144
	ds_read_b128 v[164:167], v144 offset:1024
	ds_read_b128 v[168:171], v144 offset:2048
	ds_read_b128 v[172:175], v144 offset:3072
	v_lshl_add_u64 v[144:145], s[6:7], 0, v[138:139]
	s_add_i32 m0, s65, 0xc000
	ds_read_b128 v[176:179], v147
	ds_read_b128 v[180:183], v147 offset:1024
	ds_read_b128 v[188:191], v147 offset:2048
	ds_read_b128 v[192:195], v147 offset:3072
	ds_read_b128 v[196:199], v147 offset:4096
	ds_read_b128 v[200:203], v147 offset:5120
	ds_read_b128 v[204:207], v147 offset:6144
	ds_read_b128 v[208:211], v147 offset:7168
	global_load_lds_dwordx4 v[144:145], off
	v_lshl_add_u64 v[144:145], s[6:7], 0, v[136:137]
	s_add_i32 m0, s65, 0xe000
	s_nop 0
	global_load_lds_dwordx4 v[144:145], off
	s_waitcnt vmcnt(8)
	s_waitcnt lgkmcnt(0)
	s_barrier
	s_setprio 1
	s_waitcnt lgkmcnt(0)
	v_mfma_f32_16x16x32_bf16 v[126:129], v[140:143], v[176:179], v[126:129]
	v_mfma_f32_16x16x32_bf16 v[122:125], v[152:155], v[176:179], v[122:125]
	v_mfma_f32_16x16x32_bf16 v[110:113], v[140:143], v[188:191], v[110:113]
	v_mfma_f32_16x16x32_bf16 v[106:109], v[152:155], v[188:191], v[106:109]
	v_mfma_f32_16x16x32_bf16 v[94:97], v[140:143], v[196:199], v[94:97]
	v_mfma_f32_16x16x32_bf16 v[90:93], v[152:155], v[196:199], v[90:93]
	v_mfma_f32_16x16x32_bf16 v[76:79], v[140:143], v[204:207], v[76:79]
	v_mfma_f32_16x16x32_bf16 v[72:75], v[152:155], v[204:207], v[72:75]
	v_mfma_f32_16x16x32_bf16 v[126:129], v[148:151], v[180:183], v[126:129]
	v_mfma_f32_16x16x32_bf16 v[122:125], v[156:159], v[180:183], v[122:125]
	v_mfma_f32_16x16x32_bf16 v[110:113], v[148:151], v[192:195], v[110:113]
	v_mfma_f32_16x16x32_bf16 v[106:109], v[156:159], v[192:195], v[106:109]
	v_mfma_f32_16x16x32_bf16 v[94:97], v[148:151], v[200:203], v[94:97]
	v_mfma_f32_16x16x32_bf16 v[90:93], v[156:159], v[200:203], v[90:93]
	v_mfma_f32_16x16x32_bf16 v[76:79], v[148:151], v[208:211], v[76:79]
	v_mfma_f32_16x16x32_bf16 v[72:75], v[156:159], v[208:211], v[72:75]
	v_mfma_f32_16x16x32_bf16 v[118:121], v[160:163], v[176:179], v[118:121]
	v_mfma_f32_16x16x32_bf16 v[114:117], v[168:171], v[176:179], v[114:117]
	v_mfma_f32_16x16x32_bf16 v[102:105], v[160:163], v[188:191], v[102:105]
	v_mfma_f32_16x16x32_bf16 v[98:101], v[168:171], v[188:191], v[98:101]
	v_mfma_f32_16x16x32_bf16 v[86:89], v[160:163], v[196:199], v[86:89]
	v_mfma_f32_16x16x32_bf16 v[82:85], v[168:171], v[196:199], v[82:85]
	v_mfma_f32_16x16x32_bf16 v[68:71], v[160:163], v[204:207], v[68:71]
	v_mfma_f32_16x16x32_bf16 v[64:67], v[168:171], v[204:207], v[64:67]
	v_mfma_f32_16x16x32_bf16 v[118:121], v[164:167], v[180:183], v[118:121]
	v_mfma_f32_16x16x32_bf16 v[114:117], v[172:175], v[180:183], v[114:117]
	v_mfma_f32_16x16x32_bf16 v[102:105], v[164:167], v[192:195], v[102:105]
	v_mfma_f32_16x16x32_bf16 v[98:101], v[172:175], v[192:195], v[98:101]
	v_mfma_f32_16x16x32_bf16 v[86:89], v[164:167], v[200:203], v[86:89]
	v_mfma_f32_16x16x32_bf16 v[82:85], v[172:175], v[200:203], v[82:85]
	v_mfma_f32_16x16x32_bf16 v[68:71], v[164:167], v[208:211], v[68:71]
	v_mfma_f32_16x16x32_bf16 v[64:67], v[172:175], v[208:211], v[64:67]
	s_setprio 0
	s_barrier
	s_add_i32 s26, s90, s64
	v_lshl_add_u64 v[144:145], s[38:39], 0, v[80:81]
	s_mov_b32 m0, s26
	ds_read_b128 v[176:179], v147 offset:16384
	ds_read_b128 v[180:183], v147 offset:17408
	ds_read_b128 v[188:191], v147 offset:18432
	ds_read_b128 v[192:195], v147 offset:19456
	ds_read_b128 v[196:199], v147 offset:20480
	ds_read_b128 v[200:203], v147 offset:21504
	ds_read_b128 v[204:207], v147 offset:22528
	ds_read_b128 v[208:211], v147 offset:23552
	global_load_lds_dwordx4 v[144:145], off
	s_add_i32 m0, s26, 0x2000
	s_add_u32 s26, s38, 0x40000
	v_lshl_add_u64 v[184:185], s[38:39], 0, v[130:131]
	s_addc_u32 s27, s39, 0
	s_add_i32 s90, s91, s64
	global_load_lds_dwordx4 v[184:185], off
	v_lshl_add_u64 v[186:187], s[26:27], 0, v[80:81]
	s_mov_b32 m0, s90
	v_lshl_add_u64 v[212:213], s[60:61], 0, v[132:133]
	global_load_lds_dwordx4 v[186:187], off
	v_lshl_add_u64 v[186:187], s[26:27], 0, v[130:131]
	s_add_i32 m0, s90, 0x2000
	s_nop 0
	global_load_lds_dwordx4 v[186:187], off
	v_lshl_add_u64 v[186:187], s[60:61], 0, v[134:135]
	s_mov_b32 m0, s65
	s_nop 0
	global_load_lds_dwordx4 v[186:187], off
	s_mov_b32 m0, s66
	s_nop 0
	global_load_lds_dwordx4 v[212:213], off
	s_waitcnt vmcnt(8)
	s_waitcnt lgkmcnt(0)
	s_barrier
	s_setprio 1
	s_waitcnt lgkmcnt(0)
	v_mfma_f32_16x16x32_bf16 v[60:63], v[140:143], v[176:179], v[60:63]
	v_mfma_f32_16x16x32_bf16 v[56:59], v[152:155], v[176:179], v[56:59]
	v_mfma_f32_16x16x32_bf16 v[44:47], v[140:143], v[188:191], v[44:47]
	v_mfma_f32_16x16x32_bf16 v[40:43], v[152:155], v[188:191], v[40:43]
	v_mfma_f32_16x16x32_bf16 v[28:31], v[140:143], v[196:199], v[28:31]
	v_mfma_f32_16x16x32_bf16 v[24:27], v[152:155], v[196:199], v[24:27]
	v_mfma_f32_16x16x32_bf16 v[12:15], v[140:143], v[204:207], v[12:15]
	v_mfma_f32_16x16x32_bf16 v[8:11], v[152:155], v[204:207], v[8:11]
	v_mfma_f32_16x16x32_bf16 v[60:63], v[148:151], v[180:183], v[60:63]
	v_mfma_f32_16x16x32_bf16 v[56:59], v[156:159], v[180:183], v[56:59]
	v_mfma_f32_16x16x32_bf16 v[44:47], v[148:151], v[192:195], v[44:47]
	v_mfma_f32_16x16x32_bf16 v[40:43], v[156:159], v[192:195], v[40:43]
	v_mfma_f32_16x16x32_bf16 v[28:31], v[148:151], v[200:203], v[28:31]
	v_mfma_f32_16x16x32_bf16 v[24:27], v[156:159], v[200:203], v[24:27]
	v_mfma_f32_16x16x32_bf16 v[12:15], v[148:151], v[208:211], v[12:15]
	v_mfma_f32_16x16x32_bf16 v[8:11], v[156:159], v[208:211], v[8:11]
	v_mfma_f32_16x16x32_bf16 v[52:55], v[160:163], v[176:179], v[52:55]
	v_mfma_f32_16x16x32_bf16 v[48:51], v[168:171], v[176:179], v[48:51]
	v_mfma_f32_16x16x32_bf16 v[36:39], v[160:163], v[188:191], v[36:39]
	v_mfma_f32_16x16x32_bf16 v[32:35], v[168:171], v[188:191], v[32:35]
	v_mfma_f32_16x16x32_bf16 v[20:23], v[160:163], v[196:199], v[20:23]
	v_mfma_f32_16x16x32_bf16 v[16:19], v[168:171], v[196:199], v[16:19]
	v_mfma_f32_16x16x32_bf16 v[4:7], v[160:163], v[204:207], v[4:7]
	v_mfma_f32_16x16x32_bf16 v[0:3], v[168:171], v[204:207], v[0:3]
	v_mfma_f32_16x16x32_bf16 v[52:55], v[164:167], v[180:183], v[52:55]
	v_mfma_f32_16x16x32_bf16 v[48:51], v[172:175], v[180:183], v[48:51]
	v_mfma_f32_16x16x32_bf16 v[36:39], v[164:167], v[192:195], v[36:39]
	v_mfma_f32_16x16x32_bf16 v[32:35], v[172:175], v[192:195], v[32:35]
	v_mfma_f32_16x16x32_bf16 v[20:23], v[164:167], v[200:203], v[20:23]
	v_mfma_f32_16x16x32_bf16 v[16:19], v[172:175], v[200:203], v[16:19]
	v_mfma_f32_16x16x32_bf16 v[4:7], v[164:167], v[208:211], v[4:7]
	v_mfma_f32_16x16x32_bf16 v[0:3], v[172:175], v[208:211], v[0:3]
	s_setprio 0
	s_barrier
	s_add_i32 s90, 0, 0x18000
	s_add_i32 s91, 0, 0x1c000
	v_add_u32_e32 v156, s90, v146
	v_add_u32_e32 v172, s91, v146
	ds_read_b128 v[140:143], v156
	ds_read_b128 v[148:151], v156 offset:1024
	ds_read_b128 v[152:155], v156 offset:2048
	ds_read_b128 v[156:159], v156 offset:3072
	ds_read_b128 v[160:163], v172
	ds_read_b128 v[164:167], v172 offset:1024
	ds_read_b128 v[168:171], v172 offset:2048
	ds_read_b128 v[172:175], v172 offset:3072
	s_add_u32 s26, s60, 0x40000
	s_addc_u32 s27, s61, 0
	s_mov_b32 m0, s67
	v_lshl_add_u64 v[214:215], s[26:27], 0, v[134:135]
	ds_read_b128 v[176:179], v147 offset:32768
	ds_read_b128 v[180:183], v147 offset:33792
	ds_read_b128 v[188:191], v147 offset:34816
	ds_read_b128 v[192:195], v147 offset:35840
	ds_read_b128 v[196:199], v147 offset:36864
	ds_read_b128 v[200:203], v147 offset:37888
	ds_read_b128 v[204:207], v147 offset:38912
	ds_read_b128 v[208:211], v147 offset:39936
	global_load_lds_dwordx4 v[214:215], off
	v_lshl_add_u64 v[214:215], s[26:27], 0, v[132:133]
	s_mov_b32 m0, s70
	s_nop 0
	global_load_lds_dwordx4 v[214:215], off
	s_waitcnt vmcnt(8)
	s_waitcnt lgkmcnt(0)
	s_barrier
	s_setprio 1
	s_waitcnt lgkmcnt(0)
	v_mfma_f32_16x16x32_bf16 v[126:129], v[140:143], v[176:179], v[126:129]
	v_mfma_f32_16x16x32_bf16 v[122:125], v[152:155], v[176:179], v[122:125]
	v_mfma_f32_16x16x32_bf16 v[110:113], v[140:143], v[188:191], v[110:113]
	v_mfma_f32_16x16x32_bf16 v[106:109], v[152:155], v[188:191], v[106:109]
	v_mfma_f32_16x16x32_bf16 v[94:97], v[140:143], v[196:199], v[94:97]
	v_mfma_f32_16x16x32_bf16 v[90:93], v[152:155], v[196:199], v[90:93]
	v_mfma_f32_16x16x32_bf16 v[76:79], v[140:143], v[204:207], v[76:79]
	v_mfma_f32_16x16x32_bf16 v[72:75], v[152:155], v[204:207], v[72:75]
	v_mfma_f32_16x16x32_bf16 v[126:129], v[148:151], v[180:183], v[126:129]
	v_mfma_f32_16x16x32_bf16 v[122:125], v[156:159], v[180:183], v[122:125]
	v_mfma_f32_16x16x32_bf16 v[110:113], v[148:151], v[192:195], v[110:113]
	v_mfma_f32_16x16x32_bf16 v[106:109], v[156:159], v[192:195], v[106:109]
	v_mfma_f32_16x16x32_bf16 v[94:97], v[148:151], v[200:203], v[94:97]
	v_mfma_f32_16x16x32_bf16 v[90:93], v[156:159], v[200:203], v[90:93]
	v_mfma_f32_16x16x32_bf16 v[76:79], v[148:151], v[208:211], v[76:79]
	v_mfma_f32_16x16x32_bf16 v[72:75], v[156:159], v[208:211], v[72:75]
	v_mfma_f32_16x16x32_bf16 v[118:121], v[160:163], v[176:179], v[118:121]
	v_mfma_f32_16x16x32_bf16 v[114:117], v[168:171], v[176:179], v[114:117]
	v_mfma_f32_16x16x32_bf16 v[102:105], v[160:163], v[188:191], v[102:105]
	v_mfma_f32_16x16x32_bf16 v[98:101], v[168:171], v[188:191], v[98:101]
	v_mfma_f32_16x16x32_bf16 v[86:89], v[160:163], v[196:199], v[86:89]
	v_mfma_f32_16x16x32_bf16 v[82:85], v[168:171], v[196:199], v[82:85]
	v_mfma_f32_16x16x32_bf16 v[68:71], v[160:163], v[204:207], v[68:71]
	v_mfma_f32_16x16x32_bf16 v[64:67], v[168:171], v[204:207], v[64:67]
	v_mfma_f32_16x16x32_bf16 v[118:121], v[164:167], v[180:183], v[118:121]
	v_mfma_f32_16x16x32_bf16 v[114:117], v[172:175], v[180:183], v[114:117]
	v_mfma_f32_16x16x32_bf16 v[102:105], v[164:167], v[192:195], v[102:105]
	v_mfma_f32_16x16x32_bf16 v[98:101], v[172:175], v[192:195], v[98:101]
	v_mfma_f32_16x16x32_bf16 v[86:89], v[164:167], v[200:203], v[86:89]
	v_mfma_f32_16x16x32_bf16 v[82:85], v[172:175], v[200:203], v[82:85]
	v_mfma_f32_16x16x32_bf16 v[68:71], v[164:167], v[208:211], v[68:71]
	v_mfma_f32_16x16x32_bf16 v[64:67], v[172:175], v[208:211], v[64:67]
	s_setprio 0
	s_barrier
	s_add_i32 s26, s90, s64
	v_lshl_add_u64 v[144:145], v[144:145], 0, s[12:13]
	s_mov_b32 m0, s26
	ds_read_b128 v[176:179], v147 offset:49152
	ds_read_b128 v[180:183], v147 offset:50176
	ds_read_b128 v[188:191], v147 offset:51200
	ds_read_b128 v[192:195], v147 offset:52224
	ds_read_b128 v[196:199], v147 offset:53248
	ds_read_b128 v[200:203], v147 offset:54272
	ds_read_b128 v[204:207], v147 offset:55296
	ds_read_b128 v[208:211], v147 offset:56320
	global_load_lds_dwordx4 v[144:145], off
	s_add_i32 m0, s26, 0x2000
	s_add_u32 s26, s38, 0x40080
	v_lshl_add_u64 v[144:145], v[184:185], 0, s[12:13]
	s_addc_u32 s27, s39, 0
	s_add_i32 s38, s91, s64
	global_load_lds_dwordx4 v[144:145], off
	v_lshl_add_u64 v[144:145], s[26:27], 0, v[80:81]
	s_mov_b32 m0, s38
	s_nop 0
	global_load_lds_dwordx4 v[144:145], off
	v_lshl_add_u64 v[144:145], s[26:27], 0, v[130:131]
	s_add_i32 m0, s38, 0x2000
	s_nop 0
	global_load_lds_dwordx4 v[144:145], off
	v_lshl_add_u64 v[144:145], v[186:187], 0, s[12:13]
	s_mov_b32 m0, s82
	s_nop 0
	global_load_lds_dwordx4 v[144:145], off
	v_lshl_add_u64 v[144:145], v[212:213], 0, s[12:13]
	s_mov_b32 m0, s83
	s_nop 0
	global_load_lds_dwordx4 v[144:145], off
	s_waitcnt vmcnt(8)
	s_waitcnt lgkmcnt(0)
	s_barrier
	s_setprio 1
	s_waitcnt lgkmcnt(0)
	v_mfma_f32_16x16x32_bf16 v[60:63], v[140:143], v[176:179], v[60:63]
	v_mfma_f32_16x16x32_bf16 v[56:59], v[152:155], v[176:179], v[56:59]
	v_mfma_f32_16x16x32_bf16 v[44:47], v[140:143], v[188:191], v[44:47]
	v_mfma_f32_16x16x32_bf16 v[40:43], v[152:155], v[188:191], v[40:43]
	v_mfma_f32_16x16x32_bf16 v[28:31], v[140:143], v[196:199], v[28:31]
	v_mfma_f32_16x16x32_bf16 v[24:27], v[152:155], v[196:199], v[24:27]
	v_mfma_f32_16x16x32_bf16 v[12:15], v[140:143], v[204:207], v[12:15]
	v_mfma_f32_16x16x32_bf16 v[8:11], v[152:155], v[204:207], v[8:11]
	v_mfma_f32_16x16x32_bf16 v[60:63], v[148:151], v[180:183], v[60:63]
	v_mfma_f32_16x16x32_bf16 v[56:59], v[156:159], v[180:183], v[56:59]
	v_mfma_f32_16x16x32_bf16 v[44:47], v[148:151], v[192:195], v[44:47]
	v_mfma_f32_16x16x32_bf16 v[40:43], v[156:159], v[192:195], v[40:43]
	v_mfma_f32_16x16x32_bf16 v[28:31], v[148:151], v[200:203], v[28:31]
	v_mfma_f32_16x16x32_bf16 v[24:27], v[156:159], v[200:203], v[24:27]
	v_mfma_f32_16x16x32_bf16 v[12:15], v[148:151], v[208:211], v[12:15]
	v_mfma_f32_16x16x32_bf16 v[8:11], v[156:159], v[208:211], v[8:11]
	v_mfma_f32_16x16x32_bf16 v[52:55], v[160:163], v[176:179], v[52:55]
	v_mfma_f32_16x16x32_bf16 v[48:51], v[168:171], v[176:179], v[48:51]
	v_mfma_f32_16x16x32_bf16 v[36:39], v[160:163], v[188:191], v[36:39]
	v_mfma_f32_16x16x32_bf16 v[32:35], v[168:171], v[188:191], v[32:35]
	v_mfma_f32_16x16x32_bf16 v[20:23], v[160:163], v[196:199], v[20:23]
	v_mfma_f32_16x16x32_bf16 v[16:19], v[168:171], v[196:199], v[16:19]
	v_mfma_f32_16x16x32_bf16 v[4:7], v[160:163], v[204:207], v[4:7]
	v_mfma_f32_16x16x32_bf16 v[0:3], v[168:171], v[204:207], v[0:3]
	v_mfma_f32_16x16x32_bf16 v[52:55], v[164:167], v[180:183], v[52:55]
	v_mfma_f32_16x16x32_bf16 v[48:51], v[172:175], v[180:183], v[48:51]
	v_mfma_f32_16x16x32_bf16 v[36:39], v[164:167], v[192:195], v[36:39]
	v_mfma_f32_16x16x32_bf16 v[32:35], v[172:175], v[192:195], v[32:35]
	v_mfma_f32_16x16x32_bf16 v[20:23], v[164:167], v[200:203], v[20:23]
	v_mfma_f32_16x16x32_bf16 v[16:19], v[172:175], v[200:203], v[16:19]
	v_mfma_f32_16x16x32_bf16 v[4:7], v[164:167], v[208:211], v[4:7]
	v_mfma_f32_16x16x32_bf16 v[0:3], v[172:175], v[208:211], v[0:3]
	s_setprio 0
	s_barrier
	s_add_i32 s89, s89, 2
	s_add_u32 s87, s87, 0x100
	s_addc_u32 s88, s88, 0
	s_add_u32 s6, s6, 0x100
	s_addc_u32 s7, s7, 0
	s_cmp_gt_u32 s89, 13
	s_cbranch_scc0 .LBB0_234
	s_and_b64 vcc, exec, s[10:11]
	s_cbranch_vccz .LBB0_237
	s_barrier

.LBB0_389:
	s_add_i32 s87, s6, 2
	s_add_u32 s26, s0, 0x80
	s_addc_u32 s7, s1, 0
	s_add_i32 s88, 0, 0x10000
	s_cmp_eq_u32 s84, s6
	s_cselect_b32 s7, s35, s7
	s_cselect_b32 s6, s34, s26
	v_add_u32_e32 v144, s88, v146
	s_cselect_b32 s27, s39, s31
	s_cselect_b32 s26, s38, s23
	s_add_i32 s89, 0, 0x14000
	.p2align 6
	ds_read_b128 v[140:143], v144
	ds_read_b128 v[148:151], v144 offset:1024
	ds_read_b128 v[152:155], v144 offset:2048
	ds_read_b128 v[156:159], v144 offset:3072
	v_add_u32_e32 v144, s89, v146
	ds_read_b128 v[160:163], v144
	ds_read_b128 v[164:167], v144 offset:1024
	ds_read_b128 v[168:171], v144 offset:2048
	ds_read_b128 v[172:175], v144 offset:3072
	v_lshl_add_u64 v[144:145], s[0:1], 0, v[138:139]
	s_add_i32 m0, s65, 0xc000
	ds_read_b128 v[176:179], v147
	ds_read_b128 v[180:183], v147 offset:1024
	ds_read_b128 v[188:191], v147 offset:2048
	ds_read_b128 v[192:195], v147 offset:3072
	ds_read_b128 v[196:199], v147 offset:4096
	ds_read_b128 v[200:203], v147 offset:5120
	ds_read_b128 v[204:207], v147 offset:6144
	ds_read_b128 v[208:211], v147 offset:7168
	global_load_lds_dwordx4 v[144:145], off
	v_lshl_add_u64 v[144:145], s[0:1], 0, v[136:137]
	s_add_i32 m0, s65, 0xe000
	s_nop 0
	global_load_lds_dwordx4 v[144:145], off
	s_waitcnt vmcnt(8)
	s_waitcnt lgkmcnt(0)
	s_barrier
	s_setprio 1
	s_waitcnt lgkmcnt(0)
	v_mfma_f32_16x16x32_bf16 v[126:129], v[140:143], v[176:179], v[126:129]
	v_mfma_f32_16x16x32_bf16 v[122:125], v[152:155], v[176:179], v[122:125]
	v_mfma_f32_16x16x32_bf16 v[114:117], v[140:143], v[188:191], v[114:117]
	v_mfma_f32_16x16x32_bf16 v[106:109], v[152:155], v[188:191], v[106:109]
	v_mfma_f32_16x16x32_bf16 v[98:101], v[140:143], v[196:199], v[98:101]
	v_mfma_f32_16x16x32_bf16 v[90:93], v[152:155], v[196:199], v[90:93]
	v_mfma_f32_16x16x32_bf16 v[82:85], v[140:143], v[204:207], v[82:85]
	v_mfma_f32_16x16x32_bf16 v[72:75], v[152:155], v[204:207], v[72:75]
	v_mfma_f32_16x16x32_bf16 v[126:129], v[148:151], v[180:183], v[126:129]
	v_mfma_f32_16x16x32_bf16 v[122:125], v[156:159], v[180:183], v[122:125]
	v_mfma_f32_16x16x32_bf16 v[114:117], v[148:151], v[192:195], v[114:117]
	v_mfma_f32_16x16x32_bf16 v[106:109], v[156:159], v[192:195], v[106:109]
	v_mfma_f32_16x16x32_bf16 v[98:101], v[148:151], v[200:203], v[98:101]
	v_mfma_f32_16x16x32_bf16 v[90:93], v[156:159], v[200:203], v[90:93]
	v_mfma_f32_16x16x32_bf16 v[82:85], v[148:151], v[208:211], v[82:85]
	v_mfma_f32_16x16x32_bf16 v[72:75], v[156:159], v[208:211], v[72:75]
	v_mfma_f32_16x16x32_bf16 v[118:121], v[160:163], v[176:179], v[118:121]
	v_mfma_f32_16x16x32_bf16 v[110:113], v[168:171], v[176:179], v[110:113]
	v_mfma_f32_16x16x32_bf16 v[102:105], v[160:163], v[188:191], v[102:105]
	v_mfma_f32_16x16x32_bf16 v[94:97], v[168:171], v[188:191], v[94:97]
	v_mfma_f32_16x16x32_bf16 v[86:89], v[160:163], v[196:199], v[86:89]
	v_mfma_f32_16x16x32_bf16 v[76:79], v[168:171], v[196:199], v[76:79]
	v_mfma_f32_16x16x32_bf16 v[68:71], v[160:163], v[204:207], v[68:71]
	v_mfma_f32_16x16x32_bf16 v[64:67], v[168:171], v[204:207], v[64:67]
	v_mfma_f32_16x16x32_bf16 v[118:121], v[164:167], v[180:183], v[118:121]
	v_mfma_f32_16x16x32_bf16 v[110:113], v[172:175], v[180:183], v[110:113]
	v_mfma_f32_16x16x32_bf16 v[102:105], v[164:167], v[192:195], v[102:105]
	v_mfma_f32_16x16x32_bf16 v[94:97], v[172:175], v[192:195], v[94:97]
	v_mfma_f32_16x16x32_bf16 v[86:89], v[164:167], v[200:203], v[86:89]
	v_mfma_f32_16x16x32_bf16 v[76:79], v[172:175], v[200:203], v[76:79]
	v_mfma_f32_16x16x32_bf16 v[68:71], v[164:167], v[208:211], v[68:71]
	v_mfma_f32_16x16x32_bf16 v[64:67], v[172:175], v[208:211], v[64:67]
	s_setprio 0
	s_barrier
	s_add_i32 s88, s88, s63
	v_lshl_add_u64 v[144:145], s[26:27], 0, v[80:81]
	s_mov_b32 m0, s88
	ds_read_b128 v[176:179], v147 offset:16384
	ds_read_b128 v[180:183], v147 offset:17408
	ds_read_b128 v[188:191], v147 offset:18432
	ds_read_b128 v[192:195], v147 offset:19456
	ds_read_b128 v[196:199], v147 offset:20480
	ds_read_b128 v[200:203], v147 offset:21504
	ds_read_b128 v[204:207], v147 offset:22528
	ds_read_b128 v[208:211], v147 offset:23552
	global_load_lds_dwordx4 v[144:145], off
	s_add_i32 m0, s88, 0x2000
	v_lshl_add_u64 v[184:185], s[26:27], 0, v[130:131]
	s_add_u32 s26, s26, s18
	s_addc_u32 s27, s27, 0
	s_add_i32 s88, s89, s63
	global_load_lds_dwordx4 v[184:185], off
	v_lshl_add_u64 v[186:187], s[26:27], 0, v[80:81]
	s_mov_b32 m0, s88
	v_lshl_add_u64 v[212:213], s[26:27], 0, v[130:131]
	global_load_lds_dwordx4 v[186:187], off
	s_add_i32 m0, s88, 0x2000
	v_lshl_add_u64 v[214:215], s[6:7], 0, v[134:135]
	global_load_lds_dwordx4 v[212:213], off
	s_mov_b32 m0, s65
	v_lshl_add_u64 v[220:221], s[6:7], 0, v[132:133]
	global_load_lds_dwordx4 v[214:215], off
	s_mov_b32 m0, s66
	s_nop 0
	global_load_lds_dwordx4 v[220:221], off
	s_waitcnt vmcnt(8)
	s_waitcnt lgkmcnt(0)
	s_barrier
	s_setprio 1
	s_waitcnt lgkmcnt(0)
	v_mfma_f32_16x16x32_bf16 v[60:63], v[140:143], v[176:179], v[60:63]
	v_mfma_f32_16x16x32_bf16 v[56:59], v[152:155], v[176:179], v[56:59]
	v_mfma_f32_16x16x32_bf16 v[48:51], v[140:143], v[188:191], v[48:51]
	v_mfma_f32_16x16x32_bf16 v[40:43], v[152:155], v[188:191], v[40:43]
	v_mfma_f32_16x16x32_bf16 v[32:35], v[140:143], v[196:199], v[32:35]
	v_mfma_f32_16x16x32_bf16 v[24:27], v[152:155], v[196:199], v[24:27]
	v_mfma_f32_16x16x32_bf16 v[16:19], v[140:143], v[204:207], v[16:19]
	v_mfma_f32_16x16x32_bf16 v[8:11], v[152:155], v[204:207], v[8:11]
	v_mfma_f32_16x16x32_bf16 v[60:63], v[148:151], v[180:183], v[60:63]
	v_mfma_f32_16x16x32_bf16 v[56:59], v[156:159], v[180:183], v[56:59]
	v_mfma_f32_16x16x32_bf16 v[48:51], v[148:151], v[192:195], v[48:51]
	v_mfma_f32_16x16x32_bf16 v[40:43], v[156:159], v[192:195], v[40:43]
	v_mfma_f32_16x16x32_bf16 v[32:35], v[148:151], v[200:203], v[32:35]
	v_mfma_f32_16x16x32_bf16 v[24:27], v[156:159], v[200:203], v[24:27]
	v_mfma_f32_16x16x32_bf16 v[16:19], v[148:151], v[208:211], v[16:19]
	v_mfma_f32_16x16x32_bf16 v[8:11], v[156:159], v[208:211], v[8:11]
	v_mfma_f32_16x16x32_bf16 v[52:55], v[160:163], v[176:179], v[52:55]
	v_mfma_f32_16x16x32_bf16 v[44:47], v[168:171], v[176:179], v[44:47]
	v_mfma_f32_16x16x32_bf16 v[36:39], v[160:163], v[188:191], v[36:39]
	v_mfma_f32_16x16x32_bf16 v[28:31], v[168:171], v[188:191], v[28:31]
	v_mfma_f32_16x16x32_bf16 v[20:23], v[160:163], v[196:199], v[20:23]
	v_mfma_f32_16x16x32_bf16 v[12:15], v[168:171], v[196:199], v[12:15]
	v_mfma_f32_16x16x32_bf16 v[4:7], v[160:163], v[204:207], v[4:7]
	v_mfma_f32_16x16x32_bf16 v[0:3], v[168:171], v[204:207], v[0:3]
	v_mfma_f32_16x16x32_bf16 v[52:55], v[164:167], v[180:183], v[52:55]
	v_mfma_f32_16x16x32_bf16 v[44:47], v[172:175], v[180:183], v[44:47]
	v_mfma_f32_16x16x32_bf16 v[36:39], v[164:167], v[192:195], v[36:39]
	v_mfma_f32_16x16x32_bf16 v[28:31], v[172:175], v[192:195], v[28:31]
	v_mfma_f32_16x16x32_bf16 v[20:23], v[164:167], v[200:203], v[20:23]
	v_mfma_f32_16x16x32_bf16 v[12:15], v[172:175], v[200:203], v[12:15]
	v_mfma_f32_16x16x32_bf16 v[4:7], v[164:167], v[208:211], v[4:7]
	v_mfma_f32_16x16x32_bf16 v[0:3], v[172:175], v[208:211], v[0:3]
	s_setprio 0
	s_barrier
	s_add_i32 s26, 0, 0x18000
	s_add_i32 s27, 0, 0x1c000
	v_add_u32_e32 v156, s26, v146
	v_add_u32_e32 v172, s27, v146
	ds_read_b128 v[140:143], v156
	ds_read_b128 v[148:151], v156 offset:1024
	ds_read_b128 v[152:155], v156 offset:2048
	ds_read_b128 v[156:159], v156 offset:3072
	ds_read_b128 v[160:163], v172
	ds_read_b128 v[164:167], v172 offset:1024
	ds_read_b128 v[168:171], v172 offset:2048
	ds_read_b128 v[172:175], v172 offset:3072
	s_add_u32 s6, s6, s18
	s_addc_u32 s7, s7, 0
	s_mov_b32 m0, s67
	v_lshl_add_u64 v[222:223], s[6:7], 0, v[134:135]
	ds_read_b128 v[176:179], v147 offset:32768
	ds_read_b128 v[180:183], v147 offset:33792
	ds_read_b128 v[188:191], v147 offset:34816
	ds_read_b128 v[192:195], v147 offset:35840
	ds_read_b128 v[196:199], v147 offset:36864
	ds_read_b128 v[200:203], v147 offset:37888
	ds_read_b128 v[204:207], v147 offset:38912
	ds_read_b128 v[208:211], v147 offset:39936
	global_load_lds_dwordx4 v[222:223], off
	v_lshl_add_u64 v[222:223], s[6:7], 0, v[132:133]
	s_mov_b32 m0, s70
	s_nop 0
	global_load_lds_dwordx4 v[222:223], off
	s_waitcnt vmcnt(8)
	s_waitcnt lgkmcnt(0)
	s_barrier
	s_setprio 1
	s_waitcnt lgkmcnt(0)
	v_mfma_f32_16x16x32_bf16 v[126:129], v[140:143], v[176:179], v[126:129]
	v_mfma_f32_16x16x32_bf16 v[122:125], v[152:155], v[176:179], v[122:125]
	v_mfma_f32_16x16x32_bf16 v[114:117], v[140:143], v[188:191], v[114:117]
	v_mfma_f32_16x16x32_bf16 v[106:109], v[152:155], v[188:191], v[106:109]
	v_mfma_f32_16x16x32_bf16 v[98:101], v[140:143], v[196:199], v[98:101]
	v_mfma_f32_16x16x32_bf16 v[90:93], v[152:155], v[196:199], v[90:93]
	v_mfma_f32_16x16x32_bf16 v[82:85], v[140:143], v[204:207], v[82:85]
	v_mfma_f32_16x16x32_bf16 v[72:75], v[152:155], v[204:207], v[72:75]
	v_mfma_f32_16x16x32_bf16 v[126:129], v[148:151], v[180:183], v[126:129]
	v_mfma_f32_16x16x32_bf16 v[122:125], v[156:159], v[180:183], v[122:125]
	v_mfma_f32_16x16x32_bf16 v[114:117], v[148:151], v[192:195], v[114:117]
	v_mfma_f32_16x16x32_bf16 v[106:109], v[156:159], v[192:195], v[106:109]
	v_mfma_f32_16x16x32_bf16 v[98:101], v[148:151], v[200:203], v[98:101]
	v_mfma_f32_16x16x32_bf16 v[90:93], v[156:159], v[200:203], v[90:93]
	v_mfma_f32_16x16x32_bf16 v[82:85], v[148:151], v[208:211], v[82:85]
	v_mfma_f32_16x16x32_bf16 v[72:75], v[156:159], v[208:211], v[72:75]
	v_mfma_f32_16x16x32_bf16 v[118:121], v[160:163], v[176:179], v[118:121]
	v_mfma_f32_16x16x32_bf16 v[110:113], v[168:171], v[176:179], v[110:113]
	v_mfma_f32_16x16x32_bf16 v[102:105], v[160:163], v[188:191], v[102:105]
	v_mfma_f32_16x16x32_bf16 v[94:97], v[168:171], v[188:191], v[94:97]
	v_mfma_f32_16x16x32_bf16 v[86:89], v[160:163], v[196:199], v[86:89]
	v_mfma_f32_16x16x32_bf16 v[76:79], v[168:171], v[196:199], v[76:79]
	v_mfma_f32_16x16x32_bf16 v[68:71], v[160:163], v[204:207], v[68:71]
	v_mfma_f32_16x16x32_bf16 v[64:67], v[168:171], v[204:207], v[64:67]
	v_mfma_f32_16x16x32_bf16 v[118:121], v[164:167], v[180:183], v[118:121]
	v_mfma_f32_16x16x32_bf16 v[110:113], v[172:175], v[180:183], v[110:113]
	v_mfma_f32_16x16x32_bf16 v[102:105], v[164:167], v[192:195], v[102:105]
	v_mfma_f32_16x16x32_bf16 v[94:97], v[172:175], v[192:195], v[94:97]
	v_mfma_f32_16x16x32_bf16 v[86:89], v[164:167], v[200:203], v[86:89]
	v_mfma_f32_16x16x32_bf16 v[76:79], v[172:175], v[200:203], v[76:79]
	v_mfma_f32_16x16x32_bf16 v[68:71], v[164:167], v[208:211], v[68:71]
	v_mfma_f32_16x16x32_bf16 v[64:67], v[172:175], v[208:211], v[64:67]
	s_setprio 0
	s_barrier
	s_add_i32 s6, s26, s63
	v_lshl_add_u64 v[144:145], v[144:145], 0, s[12:13]
	s_mov_b32 m0, s6
	ds_read_b128 v[176:179], v147 offset:49152
	ds_read_b128 v[180:183], v147 offset:50176
	ds_read_b128 v[188:191], v147 offset:51200
	ds_read_b128 v[192:195], v147 offset:52224
	ds_read_b128 v[196:199], v147 offset:53248
	ds_read_b128 v[200:203], v147 offset:54272
	ds_read_b128 v[204:207], v147 offset:55296
	ds_read_b128 v[208:211], v147 offset:56320
	global_load_lds_dwordx4 v[144:145], off
	v_lshl_add_u64 v[144:145], v[184:185], 0, s[12:13]
	s_add_i32 m0, s6, 0x2000
	s_add_i32 s6, s27, s63
	global_load_lds_dwordx4 v[144:145], off
	v_lshl_add_u64 v[144:145], v[186:187], 0, s[12:13]
	s_mov_b32 m0, s6
	s_nop 0
	global_load_lds_dwordx4 v[144:145], off
	v_lshl_add_u64 v[144:145], v[212:213], 0, s[12:13]
	s_add_i32 m0, s6, 0x2000
	s_nop 0
	global_load_lds_dwordx4 v[144:145], off
	v_lshl_add_u64 v[144:145], v[214:215], 0, s[12:13]
	s_mov_b32 m0, s82
	s_nop 0
	global_load_lds_dwordx4 v[144:145], off
	v_lshl_add_u64 v[144:145], v[220:221], 0, s[12:13]
	s_mov_b32 m0, s83
	s_nop 0
	global_load_lds_dwordx4 v[144:145], off
	s_waitcnt vmcnt(8)
	s_waitcnt lgkmcnt(0)
	s_barrier
	s_setprio 1
	s_waitcnt lgkmcnt(0)
	v_mfma_f32_16x16x32_bf16 v[60:63], v[140:143], v[176:179], v[60:63]
	v_mfma_f32_16x16x32_bf16 v[56:59], v[152:155], v[176:179], v[56:59]
	v_mfma_f32_16x16x32_bf16 v[48:51], v[140:143], v[188:191], v[48:51]
	v_mfma_f32_16x16x32_bf16 v[40:43], v[152:155], v[188:191], v[40:43]
	v_mfma_f32_16x16x32_bf16 v[32:35], v[140:143], v[196:199], v[32:35]
	v_mfma_f32_16x16x32_bf16 v[24:27], v[152:155], v[196:199], v[24:27]
	v_mfma_f32_16x16x32_bf16 v[16:19], v[140:143], v[204:207], v[16:19]
	v_mfma_f32_16x16x32_bf16 v[8:11], v[152:155], v[204:207], v[8:11]
	v_mfma_f32_16x16x32_bf16 v[60:63], v[148:151], v[180:183], v[60:63]
	v_mfma_f32_16x16x32_bf16 v[56:59], v[156:159], v[180:183], v[56:59]
	v_mfma_f32_16x16x32_bf16 v[48:51], v[148:151], v[192:195], v[48:51]
	v_mfma_f32_16x16x32_bf16 v[40:43], v[156:159], v[192:195], v[40:43]
	v_mfma_f32_16x16x32_bf16 v[32:35], v[148:151], v[200:203], v[32:35]
	v_mfma_f32_16x16x32_bf16 v[24:27], v[156:159], v[200:203], v[24:27]
	v_mfma_f32_16x16x32_bf16 v[16:19], v[148:151], v[208:211], v[16:19]
	v_mfma_f32_16x16x32_bf16 v[8:11], v[156:159], v[208:211], v[8:11]
	v_mfma_f32_16x16x32_bf16 v[52:55], v[160:163], v[176:179], v[52:55]
	v_mfma_f32_16x16x32_bf16 v[44:47], v[168:171], v[176:179], v[44:47]
	v_mfma_f32_16x16x32_bf16 v[36:39], v[160:163], v[188:191], v[36:39]
	v_mfma_f32_16x16x32_bf16 v[28:31], v[168:171], v[188:191], v[28:31]
	v_mfma_f32_16x16x32_bf16 v[20:23], v[160:163], v[196:199], v[20:23]
	v_mfma_f32_16x16x32_bf16 v[12:15], v[168:171], v[196:199], v[12:15]
	v_mfma_f32_16x16x32_bf16 v[4:7], v[160:163], v[204:207], v[4:7]
	v_mfma_f32_16x16x32_bf16 v[0:3], v[168:171], v[204:207], v[0:3]
	v_mfma_f32_16x16x32_bf16 v[52:55], v[164:167], v[180:183], v[52:55]
	v_mfma_f32_16x16x32_bf16 v[44:47], v[172:175], v[180:183], v[44:47]
	v_mfma_f32_16x16x32_bf16 v[36:39], v[164:167], v[192:195], v[36:39]
	v_mfma_f32_16x16x32_bf16 v[28:31], v[172:175], v[192:195], v[28:31]
	v_mfma_f32_16x16x32_bf16 v[20:23], v[164:167], v[200:203], v[20:23]
	v_mfma_f32_16x16x32_bf16 v[12:15], v[172:175], v[200:203], v[12:15]
	v_mfma_f32_16x16x32_bf16 v[4:7], v[164:167], v[208:211], v[4:7]
	v_mfma_f32_16x16x32_bf16 v[0:3], v[172:175], v[208:211], v[0:3]
	s_setprio 0
	s_barrier
	s_add_u32 s23, s23, 0x100
	s_addc_u32 s31, s31, 0
	s_add_u32 s0, s0, 0x100
	s_addc_u32 s1, s1, 0
	s_cmp_ge_u32 s87, s71
	s_mov_b32 s6, s87
	s_cbranch_scc0 .LBB0_389
	s_and_b64 vcc, exec, s[16:17]
	s_cbranch_vccz .LBB0_392
	s_barrier
